# MLA loop: -mhat folded into the QK MFMA C operand (no per-score v_sub), 2-deep LDS fragment ring, cross-tile software pipeline
# speedup vs baseline: 1.0378x; 1.0378x over previous
; __device__ __forceinline__ void attn_unit(const bf16_t* Qh, const bf16_t* Kh, const bf16_t* Vh, bf16_t* Oh  , int S, int qb, LAS unsigned char* lds, int tid) {
;     const int lane = tid & 63, r32 = lane & 31, hi = lane >> 5; const int wid = __builtin_amdgcn_readfirstlane(tid >> 6);
;     const int qrow = qb * 512 + wid * 64 + r32;
;     const bf16_t* Qw = Qh + (size_t)qrow * 96 + 8 * hi;
;     LAS unsigned char* ql = lds + QOFF + wid * 12288 + lane * 16;
; #pragma unroll
;     for (int s = 0; s < 6; ++s) { *(LAS bf16x8*)(ql + s * 1024) = GLD(bf16x8, Qw + 16 * s); *(LAS bf16x8*)(ql + (6 + s) * 1024) = GLD(bf16x8, Qw + 32 * 96 + 16 * s); }
;     const bool has1 = tid < 256; const int kc0 = tid, kc1 = has1 ? tid + 512 : tid;
;     const unsigned kd0 = (unsigned)((kc0 / 12) * KPITCH + (kc0 % 12) * 16);
;     const unsigned kd1 = has1 ? (unsigned)((kc1 / 12) * KPITCH + (kc1 % 12) * 16) : (unsigned)(DUMMY + (tid - 256) * 16);
;     const unsigned kd1n = has1 ? BUF : 0u;
;     const unsigned vd = (unsigned)(KBYTES + ((tid & 7) >> 2) * 4096 + (tid >> 3) * 64 + (tid & 3) * 16);
;     const GAS u32x4* Kg = (const GAS u32x4*)Kh; const GAS u32x4* Vg = (const GAS u32x4*)Vh;
;     const int NT = S >> 6;
;     u32x4 ka = GLD(u32x4, Kg + kc0), kb = GLD(u32x4, Kg + kc1), va = GLD(u32x4, Vg + tid);
;     *(LAS u32x4*)(lds + kd0) = ka; *(LAS u32x4*)(lds + kd1) = kb; *(LAS u32x4*)(lds + vd) = va;
;     __syncthreads();
;     f32x16 oa0 = {}, oa1 = {}, ob0 = {}, ob1 = {}; float ma = 0.f, la = 0.f, mb = 0.f, lb = 0.f;
;     const unsigned kfo = (unsigned)(r32 * KPITCH + hi * 16);
;     const unsigned vb = (unsigned)(KBYTES + ((lane >> 4) & 1) * 32 + (lane & 3) * 8 + (4 * hi + ((lane & 15) >> 2)) * 64);
;     for (int t = 0; t < NT; ++t) {
;         const unsigned cur = (unsigned)(t & 1) * BUF, nxt = BUF - cur;
;         const int tn = t + 1 < NT ? t + 1 : t;
;         ka = GLD(u32x4, Kg + (size_t)tn * 768 + kc0); kb = GLD(u32x4, Kg + (size_t)tn * 768 + kc1); va = GLD(u32x4, Vg + (size_t)tn * 512 + tid);
;         u32x4 pf[4];
;         {
;             f32x16 p0 = {}, p1 = {};
; #pragma unroll
;             for (int s = 0; s < 6; ++s) {
;                 const bf16x8 a0 = *(const LAS bf16x8*)(lds + cur + kfo + s * 32), a1 = *(const LAS bf16x8*)(lds + cur + kfo + 32 * KPITCH + s * 32);
;                 const bf16x8 q = *(const LAS bf16x8*)(ql + s * 1024);
.LBB0_76:
	s_abs_i32 s1, s24
	s_mul_hi_u32 s4, s1, s19
	s_mul_i32 s16, s4, s13
	s_sub_i32 s1, s1, s16
	s_ashr_i32 s0, s24, 31
	s_add_i32 s16, s4, 1
	s_sub_i32 s17, s1, s13
	s_cmp_ge_u32 s1, s13
	s_cselect_b32 s4, s16, s4
	s_cselect_b32 s1, s17, s1
	s_add_i32 s16, s4, 1
	s_cmp_ge_u32 s1, s13
	s_cselect_b32 s1, s16, s4
	s_xor_b32 s1, s1, s0
	s_sub_i32 s0, s1, s0
	s_mul_i32 s1, s0, s13
	s_sub_i32 s4, s24, s1
	s_ashr_i32 s1, s0, 31
	s_lshl_b64 s[26:27], s[0:1], s82
	s_mul_i32 s1, s27, 0xc0
	s_mul_hi_u32 s16, s26, 0xc0
	s_add_i32 s1, s16, s1
	s_mul_i32 s16, s26, 0xc0
	s_add_u32 s40, s96, s16
	s_addc_u32 s41, s97, s1
	s_add_u32 s16, s84, s16
	s_addc_u32 s17, s85, s1
	s_lshl_b64 s[26:27], s[26:27], 7
	s_add_u32 s26, s86, s26
	v_readfirstlane_b32 s1, v172
	s_addc_u32 s27, s87, s27
	s_lshl_b32 s4, s4, 9
	s_and_b32 s25, s1, 0xffffffc0
	s_add_i32 s4, s4, s25
	v_or_b32_e32 v136, s4, v148
	v_mov_b64_e32 v[0:1], s[40:41]
	v_mad_i64_i32 v[0:1], s[40:41], v136, s75, v[0:1]
	v_lshl_add_u64 v[40:41], v[0:1], 0, v[168:169]
	v_add_co_u32_e32 v44, vcc, s33, v40
	v_lshlrev_b64 v[60:61], 4, v[172:173]
	s_nop 0
	v_addc_co_u32_e32 v45, vcc, 0, v41, vcc
	v_lshl_add_u64 v[48:49], s[16:17], 0, v[60:61]
	global_load_dwordx4 v[0:3], v[40:41], off
	global_load_dwordx4 v[4:7], v[40:41], off offset:32
	global_load_dwordx4 v[8:11], v[40:41], off offset:64
	global_load_dwordx4 v[12:15], v[44:45], off offset:2080
	global_load_dwordx4 v[16:19], v[44:45], off offset:2112
	global_load_dwordx4 v[20:23], v[40:41], off offset:96
	global_load_dwordx4 v[24:27], v[40:41], off offset:128
	global_load_dwordx4 v[28:31], v[44:45], off offset:2144
	global_load_dwordx4 v[32:35], v[44:45], off offset:2176
	global_load_dwordx4 v[36:39], v[44:45], off offset:2048
	s_nop 0
	global_load_dwordx4 v[40:43], v[40:41], off offset:160
	s_nop 0
	global_load_dwordx4 v[44:47], v[44:45], off offset:2208
	s_nop 0
	global_load_dwordx4 v[48:51], v[48:49], off
	v_lshlrev_b64 v[62:63], 4, v[132:133]
	v_lshl_add_u64 v[52:53], s[16:17], 0, v[62:63]
	global_load_dwordx4 v[52:55], v[52:53], off
	v_lshl_add_u64 v[138:139], s[26:27], 0, v[60:61]
	global_load_dwordx4 v[56:59], v[138:139], off
	s_lshr_b32 s1, s1, 6
	s_mulk_i32 s1, 0x3000
	v_add_u32_e32 v135, s1, v149
	v_add_u32_e32 v163, 0, v150
	v_add_u32_e32 v162, 0, v157
	s_add_u32 s26, s16, 0x3000
	s_movk_i32 s1, 0x2000
	s_addc_u32 s27, s17, 0
	v_ashrrev_i32_e32 v137, 31, v136
	s_waitcnt vmcnt(0)
	ds_write_b128 v135, v[0:3] offset:43008
	s_waitcnt vmcnt(13)
	ds_write_b128 v135, v[4:7] offset:44032
	s_waitcnt vmcnt(12)
	ds_write_b128 v135, v[8:11] offset:45056
	s_waitcnt vmcnt(9)
	ds_write_b128 v135, v[20:23] offset:46080
	s_waitcnt vmcnt(8)
	ds_write_b128 v135, v[24:27] offset:47104
	s_waitcnt vmcnt(5)
	ds_write_b128 v135, v[36:39] offset:49152
	ds_write_b128 v135, v[12:15] offset:50176
	ds_write_b128 v135, v[16:19] offset:51200
	ds_write_b128 v135, v[28:31] offset:52224
	ds_write_b128 v135, v[32:35] offset:53248
	s_waitcnt vmcnt(4)
	ds_write_b128 v135, v[40:43] offset:48128
	s_waitcnt vmcnt(3)
	ds_write_b128 v135, v[44:47] offset:54272
	s_waitcnt vmcnt(2)
	ds_write_b128 v163, v[48:51]
	s_waitcnt vmcnt(1)
	ds_write_b128 v156, v[52:55]
	s_waitcnt vmcnt(0)
	ds_write_b128 v162, v[56:59] offset:13312
	s_waitcnt lgkmcnt(0)
	s_barrier
	v_mov_b64_e32 v[0:1], 0
	v_mov_b64_e32 v[2:3], 0
	v_mov_b64_e32 v[4:5], 0
	v_mov_b64_e32 v[6:7], 0
	v_mov_b64_e32 v[8:9], 0
	v_mov_b64_e32 v[10:11], 0
	v_mov_b64_e32 v[12:13], 0
	v_mov_b64_e32 v[14:15], 0
	v_mov_b64_e32 v[16:17], 0
	v_mov_b64_e32 v[18:19], 0
	v_mov_b64_e32 v[20:21], 0
	v_mov_b64_e32 v[22:23], 0
	v_mov_b64_e32 v[24:25], 0
	v_mov_b64_e32 v[26:27], 0
	v_mov_b64_e32 v[28:29], 0
	v_mov_b64_e32 v[30:31], 0
	v_mov_b64_e32 v[32:33], 0
	v_mov_b64_e32 v[34:35], 0
	v_mov_b64_e32 v[36:37], 0
	v_mov_b64_e32 v[38:39], 0
	v_mov_b64_e32 v[40:41], 0
	v_mov_b64_e32 v[42:43], 0
	v_mov_b64_e32 v[44:45], 0
	v_mov_b64_e32 v[46:47], 0
	v_mov_b64_e32 v[48:49], 0
	v_mov_b64_e32 v[50:51], 0
	v_mov_b64_e32 v[52:53], 0
	v_mov_b64_e32 v[54:55], 0
	v_mov_b64_e32 v[56:57], 0
	v_mov_b64_e32 v[58:59], 0
	v_mov_b64_e32 v[60:61], 0
	v_mov_b64_e32 v[62:63], 0
	v_mov_b32_e32 v140, 0
	v_mov_b32_e32 v141, 0
	s_mov_b32 s1, 0
	s_bitcmp1_b32 s1, 0
	s_cselect_b32 s25, 0x5400, 0
	s_sub_i32 s4, 0x5400, s25
	v_add_u32_e32 v171, s25, v155
	v_add3_u32 v184, s4, v152, v153
	v_add_u32_e32 v184, v184, v154
	ds_read_b128 v[128:131], v171
	ds_read_b128 v[142:145], v171 offset:6656
	ds_read_b128 v[162:165], v135 offset:43008
	ds_read_b128 v[176:179], v171 offset:32
	ds_read_b128 v[180:183], v171 offset:6688
	ds_read_b128 v[186:189], v135 offset:44032
	s_waitcnt lgkmcnt(3)
	v_mfma_f32_32x32x16_bf16 v[64:79], v[128:131], v[162:165], 0
	v_mfma_f32_32x32x16_bf16 v[80:95], v[142:145], v[162:165], 0
	s_mov_b32 s4, 1
	s_mul_i32 s26, s4, 0x3000
	s_mul_hi_u32 s27, s4, 0x3000
	s_add_u32 s26, s16, s26
	s_addc_u32 s27, s17, s27
	v_lshl_add_u64 v[248:249], v[172:173], 4, s[26:27]
	v_lshl_add_u64 v[250:251], v[132:133], 4, s[26:27]
	global_load_dwordx4 v[218:221], v[248:249], off
	global_load_dwordx4 v[222:225], v[250:251], off
	ds_read_b128 v[128:131], v171 offset:64
	ds_read_b128 v[142:145], v171 offset:6720
	ds_read_b128 v[162:165], v135 offset:45056
	s_waitcnt lgkmcnt(3)
	v_mfma_f32_32x32x16_bf16 v[64:79], v[176:179], v[186:189], v[64:79]
	v_mfma_f32_32x32x16_bf16 v[80:95], v[180:183], v[186:189], v[80:95]
	ds_read_b128 v[176:179], v171 offset:96
	ds_read_b128 v[180:183], v171 offset:6752
	ds_read_b128 v[186:189], v135 offset:46080
	s_waitcnt lgkmcnt(3)
; #define LAS __attribute__((address_space(3)))
; __device__ __forceinline__ float swap_max(float m) { auto rr = __builtin_amdgcn_permlane32_swap(__float_as_uint(m), __float_as_uint(m), false, false); return fmaxf(__uint_as_float(rr[0]), __uint_as_float(rr[1])); }
; __device__ __forceinline__ float max2_(float a, float b) { return __builtin_amdgcn_fmed3f(a, b, INFINITY); }
; __device__ __forceinline__ void softmax_blk(f32x16& p0, f32x16& p1, f32x16& o0, f32x16& o1, float& mhat, float& lrun, u32x4 (&pf)[4], bool first) {
;     float r0 = max2_(p0[0], p0[1]), r1 = max2_(p1[0], p1[1]);
; #pragma unroll
;     for (int e = 2; e < 16; ++e) { r0 = max2_(r0, p0[e]); r1 = max2_(r1, p1[e]); }
;     const float rm = swap_max(max2_(r0, r1));
;     if (first || __any(rm - mhat > THR)) {
;         const float mn = first ? rm : fmaxf(rm, mhat); const float f = first ? 0.f : __builtin_amdgcn_exp2f(mhat - mn); mhat = mn; lrun *= f;
; __device__ __forceinline__ void attn_unit(const bf16_t* Qh, const bf16_t* Kh, const bf16_t* Vh, bf16_t* Oh  , int S, int qb, LAS unsigned char* lds, int tid) {
;     ...
;             f32x16 p0 = {}, p1 = {};
; #pragma unroll
;             for (int s = 0; s < 6; ++s) {
;                 const bf16x8 a0 = *(const LAS bf16x8*)(lds + cur + kfo + s * 32), a1 = *(const LAS bf16x8*)(lds + cur + kfo + 32 * KPITCH + s * 32);
;                 const bf16x8 q = *(const LAS bf16x8*)(ql + s * 1024);
;                 p0 = __builtin_amdgcn_mfma_f32_32x32x16_bf16(a0, q, p0, 0, 0, 0); p1 = __builtin_amdgcn_mfma_f32_32x32x16_bf16(a1, q, p1, 0, 0, 0);
;             }
;             softmax_blk(p0, p1, oa0, oa1, ma, la, pf, t == 0);
	v_mfma_f32_32x32x16_bf16 v[64:79], v[128:131], v[162:165], v[64:79]
	v_mfma_f32_32x32x16_bf16 v[80:95], v[142:145], v[162:165], v[80:95]
	ds_read_b128 v[128:131], v171 offset:128
	ds_read_b128 v[142:145], v171 offset:6784
	ds_read_b128 v[162:165], v135 offset:47104
	s_waitcnt lgkmcnt(3)
	v_mfma_f32_32x32x16_bf16 v[64:79], v[176:179], v[186:189], v[64:79]
	v_mfma_f32_32x32x16_bf16 v[80:95], v[180:183], v[186:189], v[80:95]
	ds_read_b128 v[176:179], v171 offset:160
	ds_read_b128 v[180:183], v171 offset:6816
	ds_read_b128 v[186:189], v135 offset:48128
	s_waitcnt lgkmcnt(3)
	v_mfma_f32_32x32x16_bf16 v[64:79], v[128:131], v[162:165], v[64:79]
	v_mfma_f32_32x32x16_bf16 v[80:95], v[142:145], v[162:165], v[80:95]
	ds_read_b128 v[128:131], v171
	ds_read_b128 v[142:145], v171 offset:6656
	ds_read_b128 v[162:165], v135 offset:49152
	s_waitcnt lgkmcnt(3)
	v_mfma_f32_32x32x16_bf16 v[64:79], v[176:179], v[186:189], v[64:79]
	v_mfma_f32_32x32x16_bf16 v[80:95], v[180:183], v[186:189], v[80:95]
	ds_read_b128 v[176:179], v171 offset:32
	ds_read_b128 v[180:183], v171 offset:6688
	ds_read_b128 v[186:189], v135 offset:50176
	s_waitcnt lgkmcnt(3)
	v_mfma_f32_32x32x16_bf16 v[96:111], v[128:131], v[162:165], 0
	v_mfma_f32_32x32x16_bf16 v[112:127], v[142:145], v[162:165], 0
	s_nop 5
	v_max3_f32 v248, v64, v65, v66
	v_max3_f32 v249, v80, v81, v82
	v_max3_f32 v248, v248, v67, v68
	v_max3_f32 v249, v249, v83, v84
	v_max3_f32 v248, v248, v69, v70
	v_max3_f32 v249, v249, v85, v86
	v_max3_f32 v248, v248, v71, v72
	v_max3_f32 v249, v249, v87, v88
	v_max3_f32 v248, v248, v73, v74
	v_max3_f32 v249, v249, v89, v90
	v_max3_f32 v248, v248, v75, v76
	v_max3_f32 v249, v249, v91, v92
	v_max3_f32 v248, v248, v77, v78
	v_max3_f32 v249, v249, v93, v94
	v_max3_f32 v248, v248, v79, v95
	v_max_f32_e32 v248, v248, v249
	v_mov_b32_e32 v251, v248
	s_nop 1
	v_permlane32_swap_b32_e32 v248, v251
	v_max_f32_e32 v167, v248, v251
	v_sub_f32_e32 v64, v64, v167
	v_sub_f32_e32 v65, v65, v167
	v_sub_f32_e32 v66, v66, v167
	v_sub_f32_e32 v67, v67, v167
	v_sub_f32_e32 v68, v68, v167
	v_sub_f32_e32 v69, v69, v167
	v_sub_f32_e32 v70, v70, v167
	v_sub_f32_e32 v71, v71, v167
	v_sub_f32_e32 v72, v72, v167
	ds_read_b128 v[128:131], v171 offset:64
	ds_read_b128 v[142:145], v171 offset:6720
	ds_read_b128 v[162:165], v135 offset:51200
	s_waitcnt lgkmcnt(3)
	v_mfma_f32_32x32x16_bf16 v[96:111], v[176:179], v[186:189], v[96:111]
	v_mfma_f32_32x32x16_bf16 v[112:127], v[180:183], v[186:189], v[112:127]
	v_sub_f32_e32 v73, v73, v167
	v_sub_f32_e32 v74, v74, v167
	v_sub_f32_e32 v75, v75, v167
	v_sub_f32_e32 v76, v76, v167
	v_sub_f32_e32 v77, v77, v167
	v_sub_f32_e32 v78, v78, v167
	v_sub_f32_e32 v79, v79, v167
	v_sub_f32_e32 v80, v80, v167
	v_sub_f32_e32 v81, v81, v167
	v_sub_f32_e32 v82, v82, v167
	v_sub_f32_e32 v83, v83, v167
	v_sub_f32_e32 v84, v84, v167
	v_sub_f32_e32 v85, v85, v167
	v_sub_f32_e32 v86, v86, v167
	v_sub_f32_e32 v87, v87, v167
	v_sub_f32_e32 v88, v88, v167
	v_sub_f32_e32 v89, v89, v167
	v_sub_f32_e32 v90, v90, v167
	v_sub_f32_e32 v91, v91, v167
	v_sub_f32_e32 v92, v92, v167
	v_sub_f32_e32 v93, v93, v167
	v_sub_f32_e32 v94, v94, v167
	v_sub_f32_e32 v95, v95, v167
	v_sub_f32_e32 v232, 0, v167
	v_sub_f32_e32 v233, 0, v167
	v_sub_f32_e32 v234, 0, v167
	v_sub_f32_e32 v235, 0, v167
	v_sub_f32_e32 v236, 0, v167
	ds_read_b128 v[176:179], v171 offset:96
	ds_read_b128 v[180:183], v171 offset:6752
	ds_read_b128 v[186:189], v135 offset:52224
	s_waitcnt lgkmcnt(3)
	v_mfma_f32_32x32x16_bf16 v[96:111], v[128:131], v[162:165], v[96:111]
	v_mfma_f32_32x32x16_bf16 v[112:127], v[142:145], v[162:165], v[112:127]
	v_sub_f32_e32 v237, 0, v167
	v_sub_f32_e32 v238, 0, v167
	v_sub_f32_e32 v239, 0, v167
	v_sub_f32_e32 v240, 0, v167
	v_sub_f32_e32 v241, 0, v167
	v_sub_f32_e32 v242, 0, v167
	v_sub_f32_e32 v243, 0, v167
	v_sub_f32_e32 v244, 0, v167
	v_sub_f32_e32 v245, 0, v167
	v_sub_f32_e32 v246, 0, v167
	v_sub_f32_e32 v247, 0, v167
	v_max3_f32 v248, v64, v65, v66
	v_max3_f32 v249, v80, v81, v82
	v_max3_f32 v248, v248, v67, v68
	v_max3_f32 v249, v249, v83, v84
	v_max3_f32 v248, v248, v69, v70
	v_max3_f32 v249, v249, v85, v86
	v_max3_f32 v248, v248, v71, v72
	v_max3_f32 v249, v249, v87, v88
	v_max3_f32 v248, v248, v73, v74
	v_max3_f32 v249, v249, v89, v90
	v_max3_f32 v248, v248, v75, v76
	v_max3_f32 v249, v249, v91, v92
	v_max3_f32 v248, v248, v77, v78
	v_max3_f32 v249, v249, v93, v94
	v_max3_f32 v248, v248, v79, v95
	v_max_f32_e32 v248, v248, v249
	v_mov_b32_e32 v251, v248
	ds_read_b128 v[128:131], v171 offset:128
	ds_read_b128 v[142:145], v171 offset:6784
	ds_read_b128 v[162:165], v135 offset:53248
	s_waitcnt lgkmcnt(3)
	v_mfma_f32_32x32x16_bf16 v[96:111], v[176:179], v[186:189], v[96:111]
	v_mfma_f32_32x32x16_bf16 v[112:127], v[180:183], v[186:189], v[112:127]
	s_nop 1
	v_permlane32_swap_b32_e32 v248, v251
	v_max_f32_e32 v167, v248, v251
	v_cmp_lt_f32_e32 vcc, s72, v167
	s_cbranch_vccnz .Lmla_rescAp
; #define LAS __attribute__((address_space(3)))
; #define MLA_PACK(P, b) (u32x4){cvt_pk_bf16(P[b], P[b + 1]), cvt_pk_bf16(P[b + 2], P[b + 3]), cvt_pk_bf16(P[b + 4], P[b + 5]), cvt_pk_bf16(P[b + 6], P[b + 7])}
; __device__ __forceinline__ void softmax_blk(f32x16& p0, f32x16& p1, f32x16& o0, f32x16& o1, float& mhat, float& lrun, u32x4 (&pf)[4], bool first) {
;     ...
;     float s0 = 0.f, s1 = 0.f;
; #pragma unroll
;     for (int e = 0; e < 16; ++e) { p0[e] = __builtin_amdgcn_exp2f(p0[e] - mhat); p1[e] = __builtin_amdgcn_exp2f(p1[e] - mhat); s0 += p0[e]; s1 += p1[e]; }
;     lrun += s0 + s1;
;     pf[0] = MLA_PACK(p0, 0); pf[1] = MLA_PACK(p0, 8); pf[2] = MLA_PACK(p1, 0); pf[3] = MLA_PACK(p1, 8);
; }
; __device__ __forceinline__ void attn_unit(const bf16_t* Qh, const bf16_t* Kh, const bf16_t* Vh, bf16_t* Oh  , int S, int qb, LAS unsigned char* lds, int tid) {
;     ...
;             for (int s = 0; s < 6; ++s) {
;                 const bf16x8 a0 = *(const LAS bf16x8*)(lds + cur + kfo + s * 32), a1 = *(const LAS bf16x8*)(lds + cur + kfo + 32 * KPITCH + s * 32);
;                 const bf16x8 q = *(const LAS bf16x8*)(ql + (6 + s) * 1024);
;                 p0 = __builtin_amdgcn_mfma_f32_32x32x16_bf16(a0, q, p0, 0, 0, 0); p1 = __builtin_amdgcn_mfma_f32_32x32x16_bf16(a1, q, p1, 0, 0, 0);
;             }
;             softmax_blk(p0, p1, ob0, ob1, mb, lb, pf, t == 0);
;             pv_blk(pf, ob0, ob1, lds + cur + vb);
;         }
;         *(LAS u32x4*)(lds + nxt + kd0) = ka; *(LAS u32x4*)(lds + (has1 ? nxt : 0u) + kd1) = kb; *(LAS u32x4*)(lds + nxt + vd) = va;
;         __syncthreads();
.Lmla_rescAp_back:
	v_exp_f32_e32 v64, v64
	v_exp_f32_e32 v65, v65
	v_exp_f32_e32 v66, v66
	v_exp_f32_e32 v67, v67
	v_exp_f32_e32 v68, v68
	v_exp_f32_e32 v69, v69
	v_exp_f32_e32 v70, v70
	v_exp_f32_e32 v71, v71
	v_add_f32_e32 v166, v64, v65
	v_add_f32_e32 v140, v140, v66
	v_add_f32_e32 v166, v166, v67
	v_cvt_pk_bf16_f32 v64, v64, v65
	v_cvt_pk_bf16_f32 v65, v66, v67
	v_exp_f32_e32 v72, v72
	v_exp_f32_e32 v73, v73
	v_exp_f32_e32 v74, v74
	v_exp_f32_e32 v75, v75
	v_add_f32_e32 v140, v140, v68
	v_add_f32_e32 v166, v166, v69
	v_add_f32_e32 v140, v140, v70
	v_add_f32_e32 v166, v166, v71
	v_cvt_pk_bf16_f32 v66, v68, v69
	v_cvt_pk_bf16_f32 v67, v70, v71
	v_exp_f32_e32 v76, v76
	ds_read_b128 v[176:179], v171 offset:160
	ds_read_b128 v[180:183], v171 offset:6816
	ds_read_b128 v[186:189], v135 offset:54272
	s_waitcnt lgkmcnt(3)
	v_mfma_f32_32x32x16_bf16 v[96:111], v[128:131], v[162:165], v[96:111]
	v_mfma_f32_32x32x16_bf16 v[112:127], v[142:145], v[162:165], v[112:127]
	v_exp_f32_e32 v77, v77
	v_exp_f32_e32 v78, v78
	v_exp_f32_e32 v79, v79
	v_add_f32_e32 v140, v140, v72
	v_add_f32_e32 v166, v166, v73
	v_add_f32_e32 v140, v140, v74
	v_add_f32_e32 v166, v166, v75
	v_cvt_pk_bf16_f32 v68, v72, v73
	v_cvt_pk_bf16_f32 v69, v74, v75
	v_exp_f32_e32 v80, v80
	v_exp_f32_e32 v81, v81
	v_exp_f32_e32 v82, v82
	v_exp_f32_e32 v83, v83
	v_add_f32_e32 v140, v140, v76
	v_add_f32_e32 v166, v166, v77
	v_add_f32_e32 v140, v140, v78
	v_add_f32_e32 v166, v166, v79
	v_cvt_pk_bf16_f32 v70, v76, v77
	v_cvt_pk_bf16_f32 v71, v78, v79
	v_exp_f32_e32 v84, v84
	v_exp_f32_e32 v85, v85
	v_exp_f32_e32 v86, v86
	v_exp_f32_e32 v87, v87
	v_add_f32_e32 v140, v140, v80
	v_add_f32_e32 v166, v166, v81
	v_add_f32_e32 v140, v140, v82
	v_add_f32_e32 v166, v166, v83
	v_cvt_pk_bf16_f32 v72, v80, v81
	s_waitcnt lgkmcnt(0)
	v_mfma_f32_32x32x16_bf16 v[96:111], v[176:179], v[186:189], v[96:111]
	v_mfma_f32_32x32x16_bf16 v[112:127], v[180:183], v[186:189], v[112:127]
	v_cvt_pk_bf16_f32 v73, v82, v83
	v_exp_f32_e32 v88, v88
	v_exp_f32_e32 v89, v89
	v_exp_f32_e32 v90, v90
	v_exp_f32_e32 v91, v91
	v_add_f32_e32 v140, v140, v84
	v_add_f32_e32 v166, v166, v85
	v_add_f32_e32 v140, v140, v86
	v_add_f32_e32 v166, v166, v87
	v_cvt_pk_bf16_f32 v74, v84, v85
	v_cvt_pk_bf16_f32 v75, v86, v87
	v_exp_f32_e32 v92, v92
	v_exp_f32_e32 v93, v93
	v_exp_f32_e32 v94, v94
	v_exp_f32_e32 v95, v95
	v_add_f32_e32 v140, v140, v88
	v_add_f32_e32 v166, v166, v89
	v_add_f32_e32 v140, v140, v90
	v_add_f32_e32 v166, v166, v91
	v_cvt_pk_bf16_f32 v76, v88, v89
	v_cvt_pk_bf16_f32 v77, v90, v91
	v_add_f32_e32 v140, v140, v92
	v_add_f32_e32 v166, v166, v93
	v_add_f32_e32 v140, v140, v94
	v_add_f32_e32 v166, v166, v95
	v_cvt_pk_bf16_f32 v78, v92, v93
	v_cvt_pk_bf16_f32 v79, v94, v95
	v_add_f32_e32 v140, v140, v166
	s_nop 7
	s_nop 3
	v_max3_f32 v248, v96, v97, v98
	v_max3_f32 v249, v112, v113, v114
	v_max3_f32 v248, v248, v99, v100
	v_max3_f32 v249, v249, v115, v116
	v_max3_f32 v248, v248, v101, v102
	v_max3_f32 v249, v249, v117, v118
	v_max3_f32 v248, v248, v103, v104
	v_max3_f32 v249, v249, v119, v120
	v_max3_f32 v248, v248, v105, v106
	v_max3_f32 v249, v249, v121, v122
	v_max3_f32 v248, v248, v107, v108
	v_max3_f32 v249, v249, v123, v124
	v_max3_f32 v248, v248, v109, v110
	v_max3_f32 v249, v249, v125, v126
	v_max3_f32 v248, v248, v111, v127
	v_max_f32_e32 v248, v248, v249
	v_mov_b32_e32 v251, v248
	s_nop 1
	v_permlane32_swap_b32_e32 v248, v251
	v_max_f32_e32 v167, v248, v251
	v_sub_f32_e32 v96, v96, v167
	v_sub_f32_e32 v97, v97, v167
	v_sub_f32_e32 v98, v98, v167
	v_sub_f32_e32 v99, v99, v167
	v_sub_f32_e32 v100, v100, v167
	v_sub_f32_e32 v101, v101, v167
	v_sub_f32_e32 v102, v102, v167
	v_sub_f32_e32 v103, v103, v167
	v_sub_f32_e32 v104, v104, v167
	v_sub_f32_e32 v105, v105, v167
	v_sub_f32_e32 v106, v106, v167
	v_sub_f32_e32 v107, v107, v167
	v_sub_f32_e32 v108, v108, v167
	v_sub_f32_e32 v109, v109, v167
	v_sub_f32_e32 v110, v110, v167
	v_sub_f32_e32 v111, v111, v167
	v_sub_f32_e32 v112, v112, v167
	v_sub_f32_e32 v113, v113, v167
	v_sub_f32_e32 v114, v114, v167
	v_sub_f32_e32 v115, v115, v167
	v_sub_f32_e32 v116, v116, v167
	v_sub_f32_e32 v117, v117, v167
	v_sub_f32_e32 v118, v118, v167
	v_sub_f32_e32 v119, v119, v167
	v_sub_f32_e32 v120, v120, v167
	v_sub_f32_e32 v121, v121, v167
	v_sub_f32_e32 v122, v122, v167
	v_sub_f32_e32 v123, v123, v167
	v_sub_f32_e32 v124, v124, v167
	v_sub_f32_e32 v125, v125, v167
	v_sub_f32_e32 v126, v126, v167
	v_sub_f32_e32 v127, v127, v167
	v_sub_f32_e32 v190, 0, v167
	v_sub_f32_e32 v191, 0, v167
	v_sub_f32_e32 v192, 0, v167
	v_sub_f32_e32 v193, 0, v167
	v_sub_f32_e32 v194, 0, v167
	v_sub_f32_e32 v195, 0, v167
	v_sub_f32_e32 v196, 0, v167
	v_sub_f32_e32 v197, 0, v167
	v_sub_f32_e32 v198, 0, v167
	v_sub_f32_e32 v199, 0, v167
	v_sub_f32_e32 v200, 0, v167
	v_sub_f32_e32 v201, 0, v167
	v_sub_f32_e32 v202, 0, v167
	v_sub_f32_e32 v203, 0, v167
	v_sub_f32_e32 v204, 0, v167
	v_sub_f32_e32 v205, 0, v167
	s_sub_i32 s4, 0x5400, s25
	v_add_u32_e32 v146, s4, v150
	v_mov_b32_e32 v147, s4
	v_cndmask_b32_e64 v147, 0, v147, s[36:37]
	v_add_u32_e32 v147, v156, v147
	s_waitcnt vmcnt(1)
	ds_write_b128 v146, v[218:221]
	s_waitcnt vmcnt(0)
	ds_write_b128 v147, v[222:225]
	s_waitcnt lgkmcnt(0)
	s_barrier
	s_mov_b32 s1, 1
; #define LAS __attribute__((address_space(3)))
; __device__ __forceinline__ float swap_max(float m) { auto rr = __builtin_amdgcn_permlane32_swap(__float_as_uint(m), __float_as_uint(m), false, false); return fmaxf(__uint_as_float(rr[0]), __uint_as_float(rr[1])); }
; __device__ __forceinline__ s16x4 vtr(LAS const unsigned char* p) { return __builtin_bit_cast(s16x4, __builtin_amdgcn_ds_read_tr16_b64_v4i16((LAS s16x4*)p)); }
; #define MLA_PACK(P, b) (u32x4){cvt_pk_bf16(P[b], P[b + 1]), cvt_pk_bf16(P[b + 2], P[b + 3]), cvt_pk_bf16(P[b + 4], P[b + 5]), cvt_pk_bf16(P[b + 6], P[b + 7])}
; __device__ __forceinline__ void softmax_blk(f32x16& p0, f32x16& p1, f32x16& o0, f32x16& o1, float& mhat, float& lrun, u32x4 (&pf)[4], bool first) {
;     float r0 = max2_(p0[0], p0[1]), r1 = max2_(p1[0], p1[1]);
; #pragma unroll
;     for (int e = 2; e < 16; ++e) { r0 = max2_(r0, p0[e]); r1 = max2_(r1, p1[e]); }
;     const float rm = swap_max(max2_(r0, r1));
;     if (first || __any(rm - mhat > THR)) {
;         const float mn = first ? rm : fmaxf(rm, mhat); const float f = first ? 0.f : __builtin_amdgcn_exp2f(mhat - mn); mhat = mn; lrun *= f;
; #pragma unroll
;         for (int e = 0; e < 16; ++e) { o0[e] *= f; o1[e] *= f; }
;     }
;     float s0 = 0.f, s1 = 0.f;
; #pragma unroll
;     for (int e = 0; e < 16; ++e) { p0[e] = __builtin_amdgcn_exp2f(p0[e] - mhat); p1[e] = __builtin_amdgcn_exp2f(p1[e] - mhat); s0 += p0[e]; s1 += p1[e]; }
;     lrun += s0 + s1;
;     pf[0] = MLA_PACK(p0, 0); pf[1] = MLA_PACK(p0, 8); pf[2] = MLA_PACK(p1, 0); pf[3] = MLA_PACK(p1, 8);
; }
; __device__ __forceinline__ void pv_blk(const u32x4 (&pf)[4], f32x16& o0, f32x16& o1, LAS const unsigned char* vbase) {
; #pragma unroll
;     for (int ks = 0; ks < 4; ++ks) {
;         const bf16x8 p = __builtin_bit_cast(bf16x8, pf[ks]);
;         { const s16x4 lo = vtr(vbase + ks * 1024), hh = vtr(vbase + ks * 1024 + 512); const bf16x8 vf = {lo[0], lo[1], lo[2], lo[3], hh[0], hh[1], hh[2], hh[3]};
;           o0 = __builtin_amdgcn_mfma_f32_32x32x16_bf16(vf, p, o0, 0, 0, 0); }
;         { const s16x4 lo = vtr(vbase + 4096 + ks * 1024), hh = vtr(vbase + 4096 + ks * 1024 + 512); const bf16x8 vf = {lo[0], lo[1], lo[2], lo[3], hh[0], hh[1], hh[2], hh[3]};
;           o1 = __builtin_amdgcn_mfma_f32_32x32x16_bf16(vf, p, o1, 0, 0, 0); }
;     }
.Lmla_top:
	s_bitcmp1_b32 s1, 0
	s_cselect_b32 s25, 0x5400, 0
	s_sub_i32 s4, 0x5400, s25
	v_add_u32_e32 v171, s25, v155
	v_add3_u32 v184, s4, v152, v153
	v_add_u32_e32 v184, v184, v154
	ds_read_b64_tr_b16 v[128:129], v184 offset:13312
	ds_read_b64_tr_b16 v[130:131], v184 offset:13824
	ds_read_b64_tr_b16 v[142:143], v184 offset:17408
	ds_read_b64_tr_b16 v[144:145], v184 offset:17920
	ds_read_b64_tr_b16 v[176:177], v184 offset:14336
	ds_read_b64_tr_b16 v[178:179], v184 offset:14848
	ds_read_b64_tr_b16 v[180:181], v184 offset:18432
	ds_read_b64_tr_b16 v[182:183], v184 offset:18944
	s_waitcnt lgkmcnt(4)
	v_mfma_f32_32x32x16_bf16 v[16:31], v[128:131], v[64:67], v[16:31]
	v_mfma_f32_32x32x16_bf16 v[0:15], v[142:145], v[64:67], v[0:15]
	s_add_i32 s4, s1, 1
	s_cmp_lt_u32 s4, s18
	s_cselect_b32 s4, s4, s1
	s_mul_i32 s26, s4, 0x3000
	s_mul_hi_u32 s27, s4, 0x3000
	s_add_u32 s26, s16, s26
	s_addc_u32 s27, s17, s27
	v_lshl_add_u64 v[248:249], v[172:173], 4, s[26:27]
	v_lshl_add_u64 v[250:251], v[132:133], 4, s[26:27]
	global_load_dwordx4 v[218:221], v[248:249], off
	global_load_dwordx4 v[222:225], v[250:251], off
	s_mov_b32 s4, s1
	s_lshl_b64 s[26:27], s[4:5], 13
	v_lshl_add_u64 v[146:147], v[138:139], 0, s[26:27]
	global_load_dwordx4 v[226:229], v[146:147], off
	v_max3_f32 v248, v96, v97, v98
	v_max3_f32 v249, v112, v113, v114
	v_max3_f32 v248, v248, v99, v100
	v_max3_f32 v249, v249, v115, v116
	v_max3_f32 v248, v248, v101, v102
	v_max3_f32 v249, v249, v117, v118
	v_max3_f32 v248, v248, v103, v104
	v_max3_f32 v249, v249, v119, v120
	v_max3_f32 v248, v248, v105, v106
	v_max3_f32 v249, v249, v121, v122
	v_max3_f32 v248, v248, v107, v108
	ds_read_b64_tr_b16 v[128:129], v184 offset:15360
	ds_read_b64_tr_b16 v[130:131], v184 offset:15872
	ds_read_b64_tr_b16 v[142:143], v184 offset:19456
	ds_read_b64_tr_b16 v[144:145], v184 offset:19968
	s_waitcnt lgkmcnt(4)
	v_mfma_f32_32x32x16_bf16 v[16:31], v[176:179], v[68:71], v[16:31]
	v_mfma_f32_32x32x16_bf16 v[0:15], v[180:183], v[68:71], v[0:15]
	v_max3_f32 v249, v249, v123, v124
	v_max3_f32 v248, v248, v109, v110
	v_max3_f32 v249, v249, v125, v126
	v_max3_f32 v248, v248, v111, v127
	v_max_f32_e32 v248, v248, v249
	v_mov_b32_e32 v251, v248
	s_nop 1
	v_permlane32_swap_b32_e32 v248, v251
	v_max_f32_e32 v167, v248, v251
	v_cmp_lt_f32_e32 vcc, s72, v167
	ds_read_b64_tr_b16 v[176:177], v184 offset:16384
	ds_read_b64_tr_b16 v[178:179], v184 offset:16896
	ds_read_b64_tr_b16 v[180:181], v184 offset:20480
	ds_read_b64_tr_b16 v[182:183], v184 offset:20992
	s_waitcnt lgkmcnt(4)
	v_mfma_f32_32x32x16_bf16 v[16:31], v[128:131], v[72:75], v[16:31]
	v_mfma_f32_32x32x16_bf16 v[0:15], v[142:145], v[72:75], v[0:15]
	s_cbranch_vccnz .Lmla_rescB
.Lmla_rescB_back:
	v_exp_f32_e32 v96, v96
	v_exp_f32_e32 v97, v97
	v_exp_f32_e32 v98, v98
	v_exp_f32_e32 v99, v99
	v_exp_f32_e32 v100, v100
	v_exp_f32_e32 v101, v101
	v_exp_f32_e32 v102, v102
	v_exp_f32_e32 v103, v103
	v_add_f32_e32 v166, v96, v97
	ds_read_b128 v[128:131], v171
	ds_read_b128 v[142:145], v171 offset:6656
	ds_read_b128 v[162:165], v135 offset:43008
	s_waitcnt lgkmcnt(3)
	v_mfma_f32_32x32x16_bf16 v[16:31], v[176:179], v[76:79], v[16:31]
	v_mfma_f32_32x32x16_bf16 v[0:15], v[180:183], v[76:79], v[0:15]
	v_add_f32_e32 v141, v141, v98
	v_add_f32_e32 v166, v166, v99
	v_cvt_pk_bf16_f32 v96, v96, v97
	v_cvt_pk_bf16_f32 v97, v98, v99
	v_exp_f32_e32 v104, v104
	v_exp_f32_e32 v105, v105
	v_exp_f32_e32 v106, v106
	v_exp_f32_e32 v107, v107
	v_add_f32_e32 v141, v141, v100
	v_add_f32_e32 v166, v166, v101
	ds_read_b128 v[176:179], v171 offset:32
	ds_read_b128 v[180:183], v171 offset:6688
	ds_read_b128 v[186:189], v135 offset:44032
	s_waitcnt lgkmcnt(3)
	v_mfma_f32_32x32x16_bf16 v[64:79], v[128:131], v[162:165], v[232:247]
	v_mfma_f32_32x32x16_bf16 v[80:95], v[142:145], v[162:165], v[232:247]
	v_add_f32_e32 v141, v141, v102
	v_add_f32_e32 v166, v166, v103
	v_cvt_pk_bf16_f32 v98, v100, v101
	v_cvt_pk_bf16_f32 v99, v102, v103
	v_exp_f32_e32 v108, v108
	v_exp_f32_e32 v109, v109
	v_exp_f32_e32 v110, v110
	v_exp_f32_e32 v111, v111
	v_add_f32_e32 v141, v141, v104
	v_add_f32_e32 v166, v166, v105
	ds_read_b128 v[128:131], v171 offset:64
	ds_read_b128 v[142:145], v171 offset:6720
	ds_read_b128 v[162:165], v135 offset:45056
	s_waitcnt lgkmcnt(3)
	v_mfma_f32_32x32x16_bf16 v[64:79], v[176:179], v[186:189], v[64:79]
	v_mfma_f32_32x32x16_bf16 v[80:95], v[180:183], v[186:189], v[80:95]
	v_add_f32_e32 v141, v141, v106
	v_add_f32_e32 v166, v166, v107
	v_cvt_pk_bf16_f32 v100, v104, v105
	v_cvt_pk_bf16_f32 v101, v106, v107
	v_exp_f32_e32 v112, v112
	v_exp_f32_e32 v113, v113
	v_exp_f32_e32 v114, v114
	v_exp_f32_e32 v115, v115
	v_add_f32_e32 v141, v141, v108
	v_add_f32_e32 v166, v166, v109
	v_add_f32_e32 v141, v141, v110
	ds_read_b128 v[176:179], v171 offset:96
	ds_read_b128 v[180:183], v171 offset:6752
	ds_read_b128 v[186:189], v135 offset:46080
	s_waitcnt lgkmcnt(3)
	v_mfma_f32_32x32x16_bf16 v[64:79], v[128:131], v[162:165], v[64:79]
	v_mfma_f32_32x32x16_bf16 v[80:95], v[142:145], v[162:165], v[80:95]
	v_add_f32_e32 v166, v166, v111
	v_cvt_pk_bf16_f32 v102, v108, v109
	v_cvt_pk_bf16_f32 v103, v110, v111
	v_exp_f32_e32 v116, v116
	v_exp_f32_e32 v117, v117
	v_exp_f32_e32 v118, v118
	v_exp_f32_e32 v119, v119
	v_add_f32_e32 v141, v141, v112
	v_add_f32_e32 v166, v166, v113
	v_add_f32_e32 v141, v141, v114
	ds_read_b128 v[128:131], v171 offset:128
	ds_read_b128 v[142:145], v171 offset:6784
	ds_read_b128 v[162:165], v135 offset:47104
	s_waitcnt lgkmcnt(3)
; #define LAS __attribute__((address_space(3)))
; __device__ __forceinline__ float swap_max(float m) { auto rr = __builtin_amdgcn_permlane32_swap(__float_as_uint(m), __float_as_uint(m), false, false); return fmaxf(__uint_as_float(rr[0]), __uint_as_float(rr[1])); }
; __device__ __forceinline__ s16x4 vtr(LAS const unsigned char* p) { return __builtin_bit_cast(s16x4, __builtin_amdgcn_ds_read_tr16_b64_v4i16((LAS s16x4*)p)); }
; #define MLA_PACK(P, b) (u32x4){cvt_pk_bf16(P[b], P[b + 1]), cvt_pk_bf16(P[b + 2], P[b + 3]), cvt_pk_bf16(P[b + 4], P[b + 5]), cvt_pk_bf16(P[b + 6], P[b + 7])}
; __device__ __forceinline__ void softmax_blk(f32x16& p0, f32x16& p1, f32x16& o0, f32x16& o1, float& mhat, float& lrun, u32x4 (&pf)[4], bool first) {
;     float r0 = max2_(p0[0], p0[1]), r1 = max2_(p1[0], p1[1]);
; #pragma unroll
;     for (int e = 2; e < 16; ++e) { r0 = max2_(r0, p0[e]); r1 = max2_(r1, p1[e]); }
;     const float rm = swap_max(max2_(r0, r1));
;     if (first || __any(rm - mhat > THR)) {
;         const float mn = first ? rm : fmaxf(rm, mhat); const float f = first ? 0.f : __builtin_amdgcn_exp2f(mhat - mn); mhat = mn; lrun *= f;
; #pragma unroll
;         for (int e = 0; e < 16; ++e) { o0[e] *= f; o1[e] *= f; }
;     }
;     float s0 = 0.f, s1 = 0.f;
; #pragma unroll
;     for (int e = 0; e < 16; ++e) { p0[e] = __builtin_amdgcn_exp2f(p0[e] - mhat); p1[e] = __builtin_amdgcn_exp2f(p1[e] - mhat); s0 += p0[e]; s1 += p1[e]; }
;     lrun += s0 + s1;
;     pf[0] = MLA_PACK(p0, 0); pf[1] = MLA_PACK(p0, 8); pf[2] = MLA_PACK(p1, 0); pf[3] = MLA_PACK(p1, 8);
; }
; __device__ __forceinline__ void pv_blk(const u32x4 (&pf)[4], f32x16& o0, f32x16& o1, LAS const unsigned char* vbase) {
; #pragma unroll
;     for (int ks = 0; ks < 4; ++ks) {
;         const bf16x8 p = __builtin_bit_cast(bf16x8, pf[ks]);
;         { const s16x4 lo = vtr(vbase + ks * 1024), hh = vtr(vbase + ks * 1024 + 512); const bf16x8 vf = {lo[0], lo[1], lo[2], lo[3], hh[0], hh[1], hh[2], hh[3]};
;           o0 = __builtin_amdgcn_mfma_f32_32x32x16_bf16(vf, p, o0, 0, 0, 0); }
;         { const s16x4 lo = vtr(vbase + 4096 + ks * 1024), hh = vtr(vbase + 4096 + ks * 1024 + 512); const bf16x8 vf = {lo[0], lo[1], lo[2], lo[3], hh[0], hh[1], hh[2], hh[3]};
;           o1 = __builtin_amdgcn_mfma_f32_32x32x16_bf16(vf, p, o1, 0, 0, 0); }
;     }
	v_mfma_f32_32x32x16_bf16 v[64:79], v[176:179], v[186:189], v[64:79]
	v_mfma_f32_32x32x16_bf16 v[80:95], v[180:183], v[186:189], v[80:95]
	v_add_f32_e32 v166, v166, v115
	v_cvt_pk_bf16_f32 v104, v112, v113
	v_cvt_pk_bf16_f32 v105, v114, v115
	v_exp_f32_e32 v120, v120
	v_exp_f32_e32 v121, v121
	v_exp_f32_e32 v122, v122
	v_exp_f32_e32 v123, v123
	v_add_f32_e32 v141, v141, v116
	v_add_f32_e32 v166, v166, v117
	v_add_f32_e32 v141, v141, v118
	ds_read_b128 v[176:179], v171 offset:160
	ds_read_b128 v[180:183], v171 offset:6816
	ds_read_b128 v[186:189], v135 offset:48128
	s_waitcnt lgkmcnt(3)
	v_mfma_f32_32x32x16_bf16 v[64:79], v[128:131], v[162:165], v[64:79]
	v_mfma_f32_32x32x16_bf16 v[80:95], v[142:145], v[162:165], v[80:95]
	v_add_f32_e32 v166, v166, v119
	v_cvt_pk_bf16_f32 v106, v116, v117
	v_cvt_pk_bf16_f32 v107, v118, v119
	v_exp_f32_e32 v124, v124
	v_exp_f32_e32 v125, v125
	v_exp_f32_e32 v126, v126
	v_exp_f32_e32 v127, v127
	v_add_f32_e32 v141, v141, v120
	v_add_f32_e32 v166, v166, v121
	v_add_f32_e32 v141, v141, v122
	ds_read_b64_tr_b16 v[128:129], v184 offset:13312
	ds_read_b64_tr_b16 v[130:131], v184 offset:13824
	ds_read_b64_tr_b16 v[142:143], v184 offset:17408
	ds_read_b64_tr_b16 v[144:145], v184 offset:17920
	s_waitcnt lgkmcnt(4)
	v_mfma_f32_32x32x16_bf16 v[64:79], v[176:179], v[186:189], v[64:79]
	v_mfma_f32_32x32x16_bf16 v[80:95], v[180:183], v[186:189], v[80:95]
	v_add_f32_e32 v166, v166, v123
	v_cvt_pk_bf16_f32 v108, v120, v121
	v_cvt_pk_bf16_f32 v109, v122, v123
	v_add_f32_e32 v141, v141, v124
	v_add_f32_e32 v166, v166, v125
	v_add_f32_e32 v141, v141, v126
	v_add_f32_e32 v166, v166, v127
	v_cvt_pk_bf16_f32 v110, v124, v125
	v_cvt_pk_bf16_f32 v111, v126, v127
	v_add_f32_e32 v141, v141, v166
	ds_read_b64_tr_b16 v[176:177], v184 offset:14336
	ds_read_b64_tr_b16 v[178:179], v184 offset:14848
	ds_read_b64_tr_b16 v[180:181], v184 offset:18432
	ds_read_b64_tr_b16 v[182:183], v184 offset:18944
	s_waitcnt lgkmcnt(4)
	v_mfma_f32_32x32x16_bf16 v[48:63], v[128:131], v[96:99], v[48:63]
	v_mfma_f32_32x32x16_bf16 v[32:47], v[142:145], v[96:99], v[32:47]
	s_nop 5
	v_max3_f32 v248, v64, v65, v66
	v_max3_f32 v249, v80, v81, v82
	v_max3_f32 v248, v248, v67, v68
	v_max3_f32 v249, v249, v83, v84
	v_max3_f32 v248, v248, v69, v70
	v_max3_f32 v249, v249, v85, v86
	v_max3_f32 v248, v248, v71, v72
	v_max3_f32 v249, v249, v87, v88
	v_max3_f32 v248, v248, v73, v74
	v_max3_f32 v249, v249, v89, v90
	v_max3_f32 v248, v248, v75, v76
	ds_read_b64_tr_b16 v[128:129], v184 offset:15360
	ds_read_b64_tr_b16 v[130:131], v184 offset:15872
	ds_read_b64_tr_b16 v[142:143], v184 offset:19456
	ds_read_b64_tr_b16 v[144:145], v184 offset:19968
	s_waitcnt lgkmcnt(4)
	v_mfma_f32_32x32x16_bf16 v[48:63], v[176:179], v[100:103], v[48:63]
	v_mfma_f32_32x32x16_bf16 v[32:47], v[180:183], v[100:103], v[32:47]
	v_max3_f32 v249, v249, v91, v92
	v_max3_f32 v248, v248, v77, v78
	v_max3_f32 v249, v249, v93, v94
	v_max3_f32 v248, v248, v79, v95
	v_max_f32_e32 v248, v248, v249
	v_mov_b32_e32 v251, v248
	s_nop 1
	v_permlane32_swap_b32_e32 v248, v251
	v_max_f32_e32 v167, v248, v251
	v_cmp_lt_f32_e32 vcc, s72, v167
	ds_read_b64_tr_b16 v[176:177], v184 offset:16384
	ds_read_b64_tr_b16 v[178:179], v184 offset:16896
	ds_read_b64_tr_b16 v[180:181], v184 offset:20480
	ds_read_b64_tr_b16 v[182:183], v184 offset:20992
	s_waitcnt lgkmcnt(4)
	v_mfma_f32_32x32x16_bf16 v[48:63], v[128:131], v[104:107], v[48:63]
	v_mfma_f32_32x32x16_bf16 v[32:47], v[142:145], v[104:107], v[32:47]
	s_cbranch_vccnz .Lmla_rescA
.Lmla_rescA_back:
	v_exp_f32_e32 v64, v64
	v_exp_f32_e32 v65, v65
	v_exp_f32_e32 v66, v66
	v_exp_f32_e32 v67, v67
	v_exp_f32_e32 v68, v68
	v_exp_f32_e32 v69, v69
	v_exp_f32_e32 v70, v70
	v_exp_f32_e32 v71, v71
	v_add_f32_e32 v166, v64, v65
	ds_read_b128 v[128:131], v171
	ds_read_b128 v[142:145], v171 offset:6656
	ds_read_b128 v[162:165], v135 offset:49152
	s_waitcnt lgkmcnt(3)
	v_mfma_f32_32x32x16_bf16 v[48:63], v[176:179], v[108:111], v[48:63]
	v_mfma_f32_32x32x16_bf16 v[32:47], v[180:183], v[108:111], v[32:47]
	v_add_f32_e32 v140, v140, v66
	v_add_f32_e32 v166, v166, v67
	v_cvt_pk_bf16_f32 v64, v64, v65
	v_cvt_pk_bf16_f32 v65, v66, v67
	v_exp_f32_e32 v72, v72
	v_exp_f32_e32 v73, v73
	v_exp_f32_e32 v74, v74
	v_exp_f32_e32 v75, v75
	v_add_f32_e32 v140, v140, v68
	v_add_f32_e32 v166, v166, v69
	ds_read_b128 v[176:179], v171 offset:32
	ds_read_b128 v[180:183], v171 offset:6688
	ds_read_b128 v[186:189], v135 offset:50176
	s_waitcnt lgkmcnt(3)
	v_mfma_f32_32x32x16_bf16 v[96:111], v[128:131], v[162:165], v[190:205]
	v_mfma_f32_32x32x16_bf16 v[112:127], v[142:145], v[162:165], v[190:205]
	v_add_f32_e32 v140, v140, v70
	v_add_f32_e32 v166, v166, v71
	v_cvt_pk_bf16_f32 v66, v68, v69
	v_cvt_pk_bf16_f32 v67, v70, v71
	v_exp_f32_e32 v76, v76
	v_exp_f32_e32 v77, v77
	v_exp_f32_e32 v78, v78
	v_exp_f32_e32 v79, v79
	v_add_f32_e32 v140, v140, v72
	v_add_f32_e32 v166, v166, v73
	ds_read_b128 v[128:131], v171 offset:64
	ds_read_b128 v[142:145], v171 offset:6720
	ds_read_b128 v[162:165], v135 offset:51200
	s_waitcnt lgkmcnt(3)
	v_mfma_f32_32x32x16_bf16 v[96:111], v[176:179], v[186:189], v[96:111]
	v_mfma_f32_32x32x16_bf16 v[112:127], v[180:183], v[186:189], v[112:127]
	v_add_f32_e32 v140, v140, v74
	v_add_f32_e32 v166, v166, v75
	v_cvt_pk_bf16_f32 v68, v72, v73
	v_cvt_pk_bf16_f32 v69, v74, v75
	v_exp_f32_e32 v80, v80
	v_exp_f32_e32 v81, v81
	v_exp_f32_e32 v82, v82
	v_exp_f32_e32 v83, v83
	v_add_f32_e32 v140, v140, v76
	v_add_f32_e32 v166, v166, v77
	v_add_f32_e32 v140, v140, v78
	ds_read_b128 v[176:179], v171 offset:96
	ds_read_b128 v[180:183], v171 offset:6752
	ds_read_b128 v[186:189], v135 offset:52224
	s_waitcnt lgkmcnt(3)
; #define LAS __attribute__((address_space(3)))
; __device__ __forceinline__ float swap_max(float m) { auto rr = __builtin_amdgcn_permlane32_swap(__float_as_uint(m), __float_as_uint(m), false, false); return fmaxf(__uint_as_float(rr[0]), __uint_as_float(rr[1])); }
; #define MLA_PACK(P, b) (u32x4){cvt_pk_bf16(P[b], P[b + 1]), cvt_pk_bf16(P[b + 2], P[b + 3]), cvt_pk_bf16(P[b + 4], P[b + 5]), cvt_pk_bf16(P[b + 6], P[b + 7])}
; __device__ __forceinline__ void softmax_blk(f32x16& p0, f32x16& p1, f32x16& o0, f32x16& o1, float& mhat, float& lrun, u32x4 (&pf)[4], bool first) {
;     float r0 = max2_(p0[0], p0[1]), r1 = max2_(p1[0], p1[1]);
; #pragma unroll
;     for (int e = 2; e < 16; ++e) { r0 = max2_(r0, p0[e]); r1 = max2_(r1, p1[e]); }
;     const float rm = swap_max(max2_(r0, r1));
;     if (first || __any(rm - mhat > THR)) {
;         const float mn = first ? rm : fmaxf(rm, mhat); const float f = first ? 0.f : __builtin_amdgcn_exp2f(mhat - mn); mhat = mn; lrun *= f;
; #pragma unroll
;         for (int e = 0; e < 16; ++e) { o0[e] *= f; o1[e] *= f; }
;     }
;     float s0 = 0.f, s1 = 0.f;
; #pragma unroll
;     for (int e = 0; e < 16; ++e) { p0[e] = __builtin_amdgcn_exp2f(p0[e] - mhat); p1[e] = __builtin_amdgcn_exp2f(p1[e] - mhat); s0 += p0[e]; s1 += p1[e]; }
;     lrun += s0 + s1;
;     pf[0] = MLA_PACK(p0, 0); pf[1] = MLA_PACK(p0, 8); pf[2] = MLA_PACK(p1, 0); pf[3] = MLA_PACK(p1, 8);
; }
; __device__ __forceinline__ void attn_unit(const bf16_t* Qh, const bf16_t* Kh, const bf16_t* Vh, bf16_t* Oh  , int S, int qb, LAS unsigned char* lds, int tid) {
;     ...
;             for (int s = 0; s < 6; ++s) {
;                 const bf16x8 a0 = *(const LAS bf16x8*)(lds + cur + kfo + s * 32), a1 = *(const LAS bf16x8*)(lds + cur + kfo + 32 * KPITCH + s * 32);
;                 const bf16x8 q = *(const LAS bf16x8*)(ql + (6 + s) * 1024);
;                 p0 = __builtin_amdgcn_mfma_f32_32x32x16_bf16(a0, q, p0, 0, 0, 0); p1 = __builtin_amdgcn_mfma_f32_32x32x16_bf16(a1, q, p1, 0, 0, 0);
;             }
;             softmax_blk(p0, p1, ob0, ob1, mb, lb, pf, t == 0);
;             pv_blk(pf, ob0, ob1, lds + cur + vb);
;         }
;         *(LAS u32x4*)(lds + nxt + kd0) = ka; *(LAS u32x4*)(lds + (has1 ? nxt : 0u) + kd1) = kb; *(LAS u32x4*)(lds + nxt + vd) = va;
;         __syncthreads();
	v_mfma_f32_32x32x16_bf16 v[96:111], v[128:131], v[162:165], v[96:111]
	v_mfma_f32_32x32x16_bf16 v[112:127], v[142:145], v[162:165], v[112:127]
	v_add_f32_e32 v166, v166, v79
	v_cvt_pk_bf16_f32 v70, v76, v77
	v_cvt_pk_bf16_f32 v71, v78, v79
	v_exp_f32_e32 v84, v84
	v_exp_f32_e32 v85, v85
	v_exp_f32_e32 v86, v86
	v_exp_f32_e32 v87, v87
	v_add_f32_e32 v140, v140, v80
	v_add_f32_e32 v166, v166, v81
	v_add_f32_e32 v140, v140, v82
	ds_read_b128 v[128:131], v171 offset:128
	ds_read_b128 v[142:145], v171 offset:6784
	ds_read_b128 v[162:165], v135 offset:53248
	s_waitcnt lgkmcnt(3)
	v_mfma_f32_32x32x16_bf16 v[96:111], v[176:179], v[186:189], v[96:111]
	v_mfma_f32_32x32x16_bf16 v[112:127], v[180:183], v[186:189], v[112:127]
	v_add_f32_e32 v166, v166, v83
	v_cvt_pk_bf16_f32 v72, v80, v81
	v_cvt_pk_bf16_f32 v73, v82, v83
	v_exp_f32_e32 v88, v88
	v_exp_f32_e32 v89, v89
	v_exp_f32_e32 v90, v90
	v_exp_f32_e32 v91, v91
	v_add_f32_e32 v140, v140, v84
	v_add_f32_e32 v166, v166, v85
	v_add_f32_e32 v140, v140, v86
	s_sub_i32 s4, 0x5400, s25
	v_add_u32_e32 v146, s4, v150
	v_mov_b32_e32 v147, s4
	v_cndmask_b32_e64 v147, 0, v147, s[36:37]
	v_add_u32_e32 v147, v156, v147
	v_add_u32_e32 v167, s25, v157
	s_waitcnt vmcnt(2)
	ds_write_b128 v146, v[218:221]
	s_waitcnt vmcnt(1)
	ds_write_b128 v147, v[222:225]
	s_waitcnt vmcnt(0)
	ds_write_b128 v167, v[226:229] offset:13312
	ds_read_b128 v[176:179], v171 offset:160
	ds_read_b128 v[180:183], v171 offset:6816
	ds_read_b128 v[186:189], v135 offset:54272
	s_waitcnt lgkmcnt(6)
	v_mfma_f32_32x32x16_bf16 v[96:111], v[128:131], v[162:165], v[96:111]
	v_mfma_f32_32x32x16_bf16 v[112:127], v[142:145], v[162:165], v[112:127]
	v_add_f32_e32 v166, v166, v87
	v_cvt_pk_bf16_f32 v74, v84, v85
	v_cvt_pk_bf16_f32 v75, v86, v87
	v_exp_f32_e32 v92, v92
	v_exp_f32_e32 v93, v93
	v_exp_f32_e32 v94, v94
	v_exp_f32_e32 v95, v95
	v_add_f32_e32 v140, v140, v88
	v_add_f32_e32 v166, v166, v89
	v_add_f32_e32 v140, v140, v90
	s_waitcnt lgkmcnt(0)
	v_mfma_f32_32x32x16_bf16 v[96:111], v[176:179], v[186:189], v[96:111]
	v_mfma_f32_32x32x16_bf16 v[112:127], v[180:183], v[186:189], v[112:127]
	v_add_f32_e32 v166, v166, v91
	v_cvt_pk_bf16_f32 v76, v88, v89
	v_cvt_pk_bf16_f32 v77, v90, v91
	v_add_f32_e32 v140, v140, v92
	v_add_f32_e32 v166, v166, v93
	v_add_f32_e32 v140, v140, v94
	v_add_f32_e32 v166, v166, v95
	v_cvt_pk_bf16_f32 v78, v92, v93
	v_cvt_pk_bf16_f32 v79, v94, v95
	v_add_f32_e32 v140, v140, v166
	s_waitcnt lgkmcnt(0)
	s_barrier
	s_add_i32 s1, s1, 1
	s_cmp_lg_u32 s1, s18
	s_cbranch_scc1 .Lmla_top
	s_bitcmp1_b32 s1, 0
	s_cselect_b32 s25, 0x5400, 0
	s_sub_i32 s4, 0x5400, s25
	v_add_u32_e32 v171, s25, v155
	v_add3_u32 v184, s4, v152, v153
	v_add_u32_e32 v184, v184, v154
	ds_read_b64_tr_b16 v[128:129], v184 offset:13312
	ds_read_b64_tr_b16 v[130:131], v184 offset:13824
	ds_read_b64_tr_b16 v[142:143], v184 offset:17408
	ds_read_b64_tr_b16 v[144:145], v184 offset:17920
	ds_read_b64_tr_b16 v[176:177], v184 offset:14336
	ds_read_b64_tr_b16 v[178:179], v184 offset:14848
	ds_read_b64_tr_b16 v[180:181], v184 offset:18432
	ds_read_b64_tr_b16 v[182:183], v184 offset:18944
	s_waitcnt lgkmcnt(4)
	v_mfma_f32_32x32x16_bf16 v[16:31], v[128:131], v[64:67], v[16:31]
	v_mfma_f32_32x32x16_bf16 v[0:15], v[142:145], v[64:67], v[0:15]
	v_max3_f32 v248, v96, v97, v98
	v_max3_f32 v249, v112, v113, v114
	v_max3_f32 v248, v248, v99, v100
	v_max3_f32 v249, v249, v115, v116
	v_max3_f32 v248, v248, v101, v102
	v_max3_f32 v249, v249, v117, v118
	v_max3_f32 v248, v248, v103, v104
	v_max3_f32 v249, v249, v119, v120
	v_max3_f32 v248, v248, v105, v106
	v_max3_f32 v249, v249, v121, v122
	v_max3_f32 v248, v248, v107, v108
	v_max3_f32 v249, v249, v123, v124
	v_max3_f32 v248, v248, v109, v110
	v_max3_f32 v249, v249, v125, v126
	v_max3_f32 v248, v248, v111, v127
	v_max_f32_e32 v248, v248, v249
	v_mov_b32_e32 v251, v248
	s_nop 1
	v_permlane32_swap_b32_e32 v248, v251
	v_max_f32_e32 v167, v248, v251
	v_cmp_lt_f32_e32 vcc, s72, v167
	s_cbranch_vccnz .Lmla_rescBe
.Lmla_rescBe_back:
	v_exp_f32_e32 v96, v96
	v_exp_f32_e32 v97, v97
	v_exp_f32_e32 v98, v98
	v_exp_f32_e32 v99, v99
	ds_read_b64_tr_b16 v[128:129], v184 offset:15360
	ds_read_b64_tr_b16 v[130:131], v184 offset:15872
	ds_read_b64_tr_b16 v[142:143], v184 offset:19456
	ds_read_b64_tr_b16 v[144:145], v184 offset:19968
	s_waitcnt lgkmcnt(4)
	v_mfma_f32_32x32x16_bf16 v[16:31], v[176:179], v[68:71], v[16:31]
	v_mfma_f32_32x32x16_bf16 v[0:15], v[180:183], v[68:71], v[0:15]
	v_exp_f32_e32 v100, v100
	v_exp_f32_e32 v101, v101
	v_exp_f32_e32 v102, v102
	v_exp_f32_e32 v103, v103
	v_add_f32_e32 v166, v96, v97
	v_add_f32_e32 v141, v141, v98
	v_add_f32_e32 v166, v166, v99
	v_cvt_pk_bf16_f32 v96, v96, v97
	v_cvt_pk_bf16_f32 v97, v98, v99
	v_exp_f32_e32 v104, v104
	v_exp_f32_e32 v105, v105
	v_exp_f32_e32 v106, v106
	v_exp_f32_e32 v107, v107
	v_add_f32_e32 v141, v141, v100
	v_add_f32_e32 v166, v166, v101
	v_add_f32_e32 v141, v141, v102
	v_add_f32_e32 v166, v166, v103
	v_cvt_pk_bf16_f32 v98, v100, v101
	v_cvt_pk_bf16_f32 v99, v102, v103
	v_exp_f32_e32 v108, v108
	v_exp_f32_e32 v109, v109
	v_exp_f32_e32 v110, v110
	v_exp_f32_e32 v111, v111
	v_add_f32_e32 v141, v141, v104
	v_add_f32_e32 v166, v166, v105
	ds_read_b64_tr_b16 v[176:177], v184 offset:16384
	ds_read_b64_tr_b16 v[178:179], v184 offset:16896
	ds_read_b64_tr_b16 v[180:181], v184 offset:20480
	ds_read_b64_tr_b16 v[182:183], v184 offset:20992
	s_waitcnt lgkmcnt(4)
; #define LAS __attribute__((address_space(3)))
; __device__ __forceinline__ s16x4 vtr(LAS const unsigned char* p) { return __builtin_bit_cast(s16x4, __builtin_amdgcn_ds_read_tr16_b64_v4i16((LAS s16x4*)p)); }
; __device__ __forceinline__ void softmax_blk(f32x16& p0, f32x16& p1, f32x16& o0, f32x16& o1, float& mhat, float& lrun, u32x4 (&pf)[4], bool first) {
;     ...
;     if (first || __any(rm - mhat > THR)) {
;         const float mn = first ? rm : fmaxf(rm, mhat); const float f = first ? 0.f : __builtin_amdgcn_exp2f(mhat - mn); mhat = mn; lrun *= f;
; #pragma unroll
;         for (int e = 0; e < 16; ++e) { o0[e] *= f; o1[e] *= f; }
;     }
; __device__ __forceinline__ void pv_blk(const u32x4 (&pf)[4], f32x16& o0, f32x16& o1, LAS const unsigned char* vbase) {
; #pragma unroll
;     for (int ks = 0; ks < 4; ++ks) {
;         const bf16x8 p = __builtin_bit_cast(bf16x8, pf[ks]);
;         { const s16x4 lo = vtr(vbase + ks * 1024), hh = vtr(vbase + ks * 1024 + 512); const bf16x8 vf = {lo[0], lo[1], lo[2], lo[3], hh[0], hh[1], hh[2], hh[3]};
;           o0 = __builtin_amdgcn_mfma_f32_32x32x16_bf16(vf, p, o0, 0, 0, 0); }
;         { const s16x4 lo = vtr(vbase + 4096 + ks * 1024), hh = vtr(vbase + 4096 + ks * 1024 + 512); const bf16x8 vf = {lo[0], lo[1], lo[2], lo[3], hh[0], hh[1], hh[2], hh[3]};
;           o1 = __builtin_amdgcn_mfma_f32_32x32x16_bf16(vf, p, o1, 0, 0, 0); }
;     }
	v_mfma_f32_32x32x16_bf16 v[16:31], v[128:131], v[72:75], v[16:31]
	v_mfma_f32_32x32x16_bf16 v[0:15], v[142:145], v[72:75], v[0:15]
	v_add_f32_e32 v141, v141, v106
	v_add_f32_e32 v166, v166, v107
	v_cvt_pk_bf16_f32 v100, v104, v105
	v_cvt_pk_bf16_f32 v101, v106, v107
	v_exp_f32_e32 v112, v112
	v_exp_f32_e32 v113, v113
	v_exp_f32_e32 v114, v114
	v_exp_f32_e32 v115, v115
	v_add_f32_e32 v141, v141, v108
	v_add_f32_e32 v166, v166, v109
	v_add_f32_e32 v141, v141, v110
	v_add_f32_e32 v166, v166, v111
	v_cvt_pk_bf16_f32 v102, v108, v109
	v_cvt_pk_bf16_f32 v103, v110, v111
	v_exp_f32_e32 v116, v116
	v_exp_f32_e32 v117, v117
	v_exp_f32_e32 v118, v118
	v_exp_f32_e32 v119, v119
	v_add_f32_e32 v141, v141, v112
	v_add_f32_e32 v166, v166, v113
	v_add_f32_e32 v141, v141, v114
	v_add_f32_e32 v166, v166, v115
	v_cvt_pk_bf16_f32 v104, v112, v113
	v_cvt_pk_bf16_f32 v105, v114, v115
	v_exp_f32_e32 v120, v120
	v_exp_f32_e32 v121, v121
	ds_read_b64_tr_b16 v[128:129], v184 offset:13312
	ds_read_b64_tr_b16 v[130:131], v184 offset:13824
	ds_read_b64_tr_b16 v[142:143], v184 offset:17408
	ds_read_b64_tr_b16 v[144:145], v184 offset:17920
	s_waitcnt lgkmcnt(4)
	v_mfma_f32_32x32x16_bf16 v[16:31], v[176:179], v[76:79], v[16:31]
	v_mfma_f32_32x32x16_bf16 v[0:15], v[180:183], v[76:79], v[0:15]
	v_exp_f32_e32 v122, v122
	v_exp_f32_e32 v123, v123
	v_add_f32_e32 v141, v141, v116
	v_add_f32_e32 v166, v166, v117
	v_add_f32_e32 v141, v141, v118
	v_add_f32_e32 v166, v166, v119
	v_cvt_pk_bf16_f32 v106, v116, v117
	v_cvt_pk_bf16_f32 v107, v118, v119
	v_exp_f32_e32 v124, v124
	v_exp_f32_e32 v125, v125
	v_exp_f32_e32 v126, v126
	v_exp_f32_e32 v127, v127
	v_add_f32_e32 v141, v141, v120
	v_add_f32_e32 v166, v166, v121
	v_add_f32_e32 v141, v141, v122
	v_add_f32_e32 v166, v166, v123
	v_cvt_pk_bf16_f32 v108, v120, v121
	v_cvt_pk_bf16_f32 v109, v122, v123
	v_add_f32_e32 v141, v141, v124
	v_add_f32_e32 v166, v166, v125
	v_add_f32_e32 v141, v141, v126
	v_add_f32_e32 v166, v166, v127
	v_cvt_pk_bf16_f32 v110, v124, v125
	v_cvt_pk_bf16_f32 v111, v126, v127
	v_add_f32_e32 v141, v141, v166
	ds_read_b64_tr_b16 v[176:177], v184 offset:14336
	ds_read_b64_tr_b16 v[178:179], v184 offset:14848
	ds_read_b64_tr_b16 v[180:181], v184 offset:18432
	ds_read_b64_tr_b16 v[182:183], v184 offset:18944
	s_waitcnt lgkmcnt(4)
	v_mfma_f32_32x32x16_bf16 v[48:63], v[128:131], v[96:99], v[48:63]
	v_mfma_f32_32x32x16_bf16 v[32:47], v[142:145], v[96:99], v[32:47]
	ds_read_b64_tr_b16 v[128:129], v184 offset:15360
	ds_read_b64_tr_b16 v[130:131], v184 offset:15872
	ds_read_b64_tr_b16 v[142:143], v184 offset:19456
	ds_read_b64_tr_b16 v[144:145], v184 offset:19968
	s_waitcnt lgkmcnt(4)
	v_mfma_f32_32x32x16_bf16 v[48:63], v[176:179], v[100:103], v[48:63]
	v_mfma_f32_32x32x16_bf16 v[32:47], v[180:183], v[100:103], v[32:47]
	ds_read_b64_tr_b16 v[176:177], v184 offset:16384
	ds_read_b64_tr_b16 v[178:179], v184 offset:16896
	ds_read_b64_tr_b16 v[180:181], v184 offset:20480
	ds_read_b64_tr_b16 v[182:183], v184 offset:20992
	s_waitcnt lgkmcnt(4)
	v_mfma_f32_32x32x16_bf16 v[48:63], v[128:131], v[104:107], v[48:63]
	v_mfma_f32_32x32x16_bf16 v[32:47], v[142:145], v[104:107], v[32:47]
	s_waitcnt lgkmcnt(0)
	v_mfma_f32_32x32x16_bf16 v[48:63], v[176:179], v[108:111], v[48:63]
	v_mfma_f32_32x32x16_bf16 v[32:47], v[180:183], v[108:111], v[32:47]
	s_waitcnt lgkmcnt(0)
	s_barrier
	s_nop 7
	s_nop 3
	s_branch .LBB0_75
.Lmla_rescAp:
	v_max_f32_e32 v249, 0, v167
	v_exp_f32_e64 v250, -v249
	s_nop 0
	v_mul_f32_e32 v140, v140, v250
	v_pk_mul_f32 v[0:1], v[0:1], v[250:251] op_sel_hi:[1,0]
	v_pk_mul_f32 v[2:3], v[2:3], v[250:251] op_sel_hi:[1,0]
	v_pk_mul_f32 v[4:5], v[4:5], v[250:251] op_sel_hi:[1,0]
	v_pk_mul_f32 v[6:7], v[6:7], v[250:251] op_sel_hi:[1,0]
	v_pk_mul_f32 v[8:9], v[8:9], v[250:251] op_sel_hi:[1,0]
	v_pk_mul_f32 v[10:11], v[10:11], v[250:251] op_sel_hi:[1,0]
	v_pk_mul_f32 v[12:13], v[12:13], v[250:251] op_sel_hi:[1,0]
	v_pk_mul_f32 v[14:15], v[14:15], v[250:251] op_sel_hi:[1,0]
	v_pk_mul_f32 v[16:17], v[16:17], v[250:251] op_sel_hi:[1,0]
	v_pk_mul_f32 v[18:19], v[18:19], v[250:251] op_sel_hi:[1,0]
	v_pk_mul_f32 v[20:21], v[20:21], v[250:251] op_sel_hi:[1,0]
	v_pk_mul_f32 v[22:23], v[22:23], v[250:251] op_sel_hi:[1,0]
	v_pk_mul_f32 v[24:25], v[24:25], v[250:251] op_sel_hi:[1,0]
	v_pk_mul_f32 v[26:27], v[26:27], v[250:251] op_sel_hi:[1,0]
	v_pk_mul_f32 v[28:29], v[28:29], v[250:251] op_sel_hi:[1,0]
	v_pk_mul_f32 v[30:31], v[30:31], v[250:251] op_sel_hi:[1,0]
	v_sub_f32_e32 v64, v64, v249
	v_sub_f32_e32 v65, v65, v249
	v_sub_f32_e32 v66, v66, v249
	v_sub_f32_e32 v67, v67, v249
	v_sub_f32_e32 v68, v68, v249
	v_sub_f32_e32 v69, v69, v249
	v_sub_f32_e32 v70, v70, v249
	v_sub_f32_e32 v71, v71, v249
	v_sub_f32_e32 v72, v72, v249
	v_sub_f32_e32 v73, v73, v249
	v_sub_f32_e32 v74, v74, v249
	v_sub_f32_e32 v75, v75, v249
	v_sub_f32_e32 v76, v76, v249
	v_sub_f32_e32 v77, v77, v249
	v_sub_f32_e32 v78, v78, v249
	v_sub_f32_e32 v79, v79, v249
	v_sub_f32_e32 v80, v80, v249
	v_sub_f32_e32 v81, v81, v249
	v_sub_f32_e32 v82, v82, v249
	v_sub_f32_e32 v83, v83, v249
	v_sub_f32_e32 v84, v84, v249
	v_sub_f32_e32 v85, v85, v249
	v_sub_f32_e32 v86, v86, v249
	v_sub_f32_e32 v87, v87, v249
	v_sub_f32_e32 v88, v88, v249
	v_sub_f32_e32 v89, v89, v249
	v_sub_f32_e32 v90, v90, v249
	v_sub_f32_e32 v91, v91, v249
	v_sub_f32_e32 v92, v92, v249
	v_sub_f32_e32 v93, v93, v249
	v_sub_f32_e32 v94, v94, v249
	v_sub_f32_e32 v95, v95, v249
	v_sub_f32_e32 v232, v232, v249
	v_sub_f32_e32 v233, v233, v249
	v_sub_f32_e32 v234, v234, v249
	v_sub_f32_e32 v235, v235, v249
	v_sub_f32_e32 v236, v236, v249
	v_sub_f32_e32 v237, v237, v249
	v_sub_f32_e32 v238, v238, v249
	v_sub_f32_e32 v239, v239, v249
	v_sub_f32_e32 v240, v240, v249
	v_sub_f32_e32 v241, v241, v249
	v_sub_f32_e32 v242, v242, v249
	v_sub_f32_e32 v243, v243, v249
	v_sub_f32_e32 v244, v244, v249
	v_sub_f32_e32 v245, v245, v249
	v_sub_f32_e32 v246, v246, v249
	v_sub_f32_e32 v247, v247, v249
	s_branch .Lmla_rescAp_back

; __device__ __forceinline__ void softmax_blk(f32x16& p0, f32x16& p1, f32x16& o0, f32x16& o1, float& mhat, float& lrun, u32x4 (&pf)[4], bool first) {
;     ...
;     if (first || __any(rm - mhat > THR)) {
;         const float mn = first ? rm : fmaxf(rm, mhat); const float f = first ? 0.f : __builtin_amdgcn_exp2f(mhat - mn); mhat = mn; lrun *= f;
; #pragma unroll
;         for (int e = 0; e < 16; ++e) { o0[e] *= f; o1[e] *= f; }
;     }
.Lmla_rescB:
	v_max_f32_e32 v249, 0, v167
	v_exp_f32_e64 v250, -v249
	s_nop 0
	v_mul_f32_e32 v141, v141, v250
	v_pk_mul_f32 v[32:33], v[32:33], v[250:251] op_sel_hi:[1,0]
	v_pk_mul_f32 v[34:35], v[34:35], v[250:251] op_sel_hi:[1,0]
	v_pk_mul_f32 v[36:37], v[36:37], v[250:251] op_sel_hi:[1,0]
	v_pk_mul_f32 v[38:39], v[38:39], v[250:251] op_sel_hi:[1,0]
	v_pk_mul_f32 v[40:41], v[40:41], v[250:251] op_sel_hi:[1,0]
	v_pk_mul_f32 v[42:43], v[42:43], v[250:251] op_sel_hi:[1,0]
	v_pk_mul_f32 v[44:45], v[44:45], v[250:251] op_sel_hi:[1,0]
	v_pk_mul_f32 v[46:47], v[46:47], v[250:251] op_sel_hi:[1,0]
	v_pk_mul_f32 v[48:49], v[48:49], v[250:251] op_sel_hi:[1,0]
	v_pk_mul_f32 v[50:51], v[50:51], v[250:251] op_sel_hi:[1,0]
	v_pk_mul_f32 v[52:53], v[52:53], v[250:251] op_sel_hi:[1,0]
	v_pk_mul_f32 v[54:55], v[54:55], v[250:251] op_sel_hi:[1,0]
	v_pk_mul_f32 v[56:57], v[56:57], v[250:251] op_sel_hi:[1,0]
	v_pk_mul_f32 v[58:59], v[58:59], v[250:251] op_sel_hi:[1,0]
	v_pk_mul_f32 v[60:61], v[60:61], v[250:251] op_sel_hi:[1,0]
	v_pk_mul_f32 v[62:63], v[62:63], v[250:251] op_sel_hi:[1,0]
	v_sub_f32_e32 v96, v96, v249
	v_sub_f32_e32 v97, v97, v249
	v_sub_f32_e32 v98, v98, v249
	v_sub_f32_e32 v99, v99, v249
	v_sub_f32_e32 v100, v100, v249
	v_sub_f32_e32 v101, v101, v249
	v_sub_f32_e32 v102, v102, v249
	v_sub_f32_e32 v103, v103, v249
	v_sub_f32_e32 v104, v104, v249
	v_sub_f32_e32 v105, v105, v249
	v_sub_f32_e32 v106, v106, v249
	v_sub_f32_e32 v107, v107, v249
	v_sub_f32_e32 v108, v108, v249
	v_sub_f32_e32 v109, v109, v249
	v_sub_f32_e32 v110, v110, v249
	v_sub_f32_e32 v111, v111, v249
	v_sub_f32_e32 v112, v112, v249
	v_sub_f32_e32 v113, v113, v249
	v_sub_f32_e32 v114, v114, v249
	v_sub_f32_e32 v115, v115, v249
	v_sub_f32_e32 v116, v116, v249
	v_sub_f32_e32 v117, v117, v249
	v_sub_f32_e32 v118, v118, v249
	v_sub_f32_e32 v119, v119, v249
	v_sub_f32_e32 v120, v120, v249
	v_sub_f32_e32 v121, v121, v249
	v_sub_f32_e32 v122, v122, v249
	v_sub_f32_e32 v123, v123, v249
	v_sub_f32_e32 v124, v124, v249
	v_sub_f32_e32 v125, v125, v249
	v_sub_f32_e32 v126, v126, v249
	v_sub_f32_e32 v127, v127, v249
	v_sub_f32_e32 v190, v190, v249
	v_sub_f32_e32 v191, v191, v249
	v_sub_f32_e32 v192, v192, v249
	v_sub_f32_e32 v193, v193, v249
	v_sub_f32_e32 v194, v194, v249
	v_sub_f32_e32 v195, v195, v249
	v_sub_f32_e32 v196, v196, v249
	v_sub_f32_e32 v197, v197, v249
	v_sub_f32_e32 v198, v198, v249
	v_sub_f32_e32 v199, v199, v249
	v_sub_f32_e32 v200, v200, v249
	v_sub_f32_e32 v201, v201, v249
	v_sub_f32_e32 v202, v202, v249
	v_sub_f32_e32 v203, v203, v249
	v_sub_f32_e32 v204, v204, v249
	v_sub_f32_e32 v205, v205, v249
	s_branch .Lmla_rescB_back
